# SB fast path: remaining copy moves removed by issuing the next exp before the rcp so rcp writes its final register directly
# speedup vs baseline: 1.0060x; 1.0060x over previous
; DI int crow(int reg, int hh) { return (reg & 3) + 8 * (reg >> 2) + 4 * hh; }
; DI float ex2(float x) { return __builtin_amdgcn_exp2f(x); }
; DI void sb_item(const bf16_t* __restrict__ P, const bf16_t* __restrict__ VT, bf16_t* __restrict__ Y, int item, char* lds) {
;     ...
;   auto do_tile = [&](int kb, const bf16_t* kcur) {
;     const bool active = (kb * 64 < q0 + 31) && (__ballot(carry > 0.f) != 0ull);
;     if (active) {
;       qk_tile(kcur, qf, S, l32, hh);
;       const bool full = kb * 64 + 63 < q0;
; #pragma unroll
;     ...
;         float st[16];
; #pragma unroll
;         for (int e = 0; e < 16; ++e) {
;           const float ez = ex2(S[kt2][e]);
;           const float r = __builtin_amdgcn_rcpf(1.f + ez);
;           const bool vis = full || (kb * 64 + kt2 * 32 + crow(e, hh) < qpos);
;           st[e] = vis ? r : 1.f;
;           S[kt2][e] = vis ? 1.f - r : 0.f;
;         }
;     ...
;   for (int kb = kbs; kb >= 1; kb -= 2) {
;     const bf16_t* bcur = Ks + par * (4 * TS);
;     bf16_t* bnxt = Ks + (par ^ 1) * (4 * TS);
;     tile_commit(bnxt, pfk); tile_commit(bnxt + TS, pfv); tile_commit(bnxt + 2 * TS, pfk1); tile_commit(bnxt + 3 * TS, pfv1);
;     {
;       const int f0 = kb >= 5 ? kb - 4 : 1, f1 = kb >= 5 ? kb - 5 : 0;
;       pfk = tile_fetch(kb0 + (size_t)f0 * 64 * LDP_O, LDP_O); pfv = tile_fetch(vb0 + f0 * 64, SEQ);
;       pfk1 = tile_fetch(kb0 + (size_t)f1 * 64 * LDP_O, LDP_O); pfv1 = tile_fetch(vb0 + f1 * 64, SEQ);
;       __builtin_amdgcn_sched_barrier(0); }
.LBB0_485:
	s_mul_i32 s14, s12, 0x9000
	s_xor_b32 s12, s12, 1
	s_mul_i32 s0, s12, 0x9000
	v_add_u32_e32 v0, s0, v242
	s_add_i32 s9, s9, -2
	s_waitcnt vmcnt(3)
	ds_write_b128 v0, v[96:99]
	s_waitcnt vmcnt(2)
	ds_write_b128 v0, v[100:103] offset:9216
	s_waitcnt vmcnt(1)
	ds_write_b128 v0, v[104:107] offset:18432
	s_waitcnt vmcnt(0)
	ds_write_b128 v0, v[108:111] offset:27648
	s_max_u32 s0, s9, 5
	s_add_i32 s28, s0, -4
	s_lshl_b64 s[0:1], s[28:29], 18
	s_add_u32 s0, s44, s0
	s_addc_u32 s1, s45, s1
	global_load_dwordx4 v[96:99], v243, s[0:1] offset:2048
	s_lshl_b32 s28, s28, 6
	s_lshl_b64 s[0:1], s[28:29], 1
	s_add_u32 s0, s46, s0
	s_addc_u32 s1, s47, s1
	global_load_dwordx4 v[100:103], v244, s[0:1]
	s_sub_i32 s28, s9, 5
	s_max_i32 s28, s28, 0
	s_lshl_b64 s[0:1], s[28:29], 18
	s_add_u32 s0, s44, s0
	s_addc_u32 s1, s45, s1
	global_load_dwordx4 v[104:107], v243, s[0:1] offset:2048
	s_lshl_b32 s28, s28, 6
	s_lshl_b64 s[0:1], s[28:29], 1
	s_add_u32 s0, s46, s0
	s_addc_u32 s1, s47, s1
	global_load_dwordx4 v[108:111], v244, s[0:1]
	s_sub_i32 s0, s10, 63
	v_cmp_lt_i32_e32 vcc, s0, v119
	s_and_saveexec_b64 s[48:49], vcc
	s_cbranch_execz .LBB0_488
	v_cmp_lt_f32_e32 vcc, 0, v117
	s_cbranch_vccz .LBB0_488
	v_lshl_add_u32 v0, v121, 1, s14
	ds_read_b128 v[2:5], v0
	ds_read_b128 v[6:9], v0 offset:32
	ds_read_b128 v[10:13], v0 offset:64
	ds_read_b128 v[122:125], v0 offset:96
	ds_read_b128 v[64:67], v0 offset:4608
	ds_read_b128 v[126:129], v0 offset:4640
	ds_read_b128 v[130:133], v0 offset:4672
	ds_read_b128 v[134:137], v0 offset:4704
	s_setprio 1
	s_waitcnt lgkmcnt(7)
	v_mfma_f32_32x32x16_bf16 v[48:63], v[2:5], v[80:83], 0
	s_waitcnt lgkmcnt(3)
	v_mfma_f32_32x32x16_bf16 v[64:79], v[64:67], v[80:83], 0
	v_mfma_f32_32x32x16_bf16 v[48:63], v[6:9], v[84:87], v[48:63]
	s_waitcnt lgkmcnt(2)
	v_mfma_f32_32x32x16_bf16 v[64:79], v[126:129], v[84:87], v[64:79]
	v_mfma_f32_32x32x16_bf16 v[48:63], v[10:13], v[88:91], v[48:63]
	s_waitcnt lgkmcnt(1)
	v_mfma_f32_32x32x16_bf16 v[64:79], v[130:133], v[88:91], v[64:79]
	v_mfma_f32_32x32x16_bf16 v[48:63], v[122:125], v[92:95], v[48:63]
	s_waitcnt lgkmcnt(0)
	v_mfma_f32_32x32x16_bf16 v[64:79], v[134:137], v[92:95], v[64:79]
	s_setprio 0
	s_nop 10
	v_exp_f32_e32 v0, v64
	v_exp_f32_e32 v2, v65
	v_add_u32_e32 v13, s10, v113
	v_subrev_u32_e32 v3, 31, v13
	v_add_f32_e32 v0, 1.0, v0
	v_rcp_f32_e32 v0, v0
	v_cmp_lt_u32_e32 vcc, s10, v118
	s_cmp_eq_u64 vcc, exec
	s_cbranch_scc0 .Lsb_slow1
	v_add_f32_e32 v2, 1.0, v2
	v_mov_b32_e32 v3, v0
	v_sub_f32_e32 v0, 1.0, v0
	v_rcp_f32_e32 v64, v2
	v_exp_f32_e32 v4, v66
	v_sub_f32_e32 v65, 1.0, v64
	v_add_f32_e32 v2, 1.0, v4
	v_rcp_f32_e32 v66, v2
	v_exp_f32_e32 v4, v67
	v_sub_f32_e32 v67, 1.0, v66
	v_add_f32_e32 v2, 1.0, v4
	v_exp_f32_e32 v4, v68
	v_rcp_f32_e32 v68, v2
	s_nop 0
	v_sub_f32_e32 v122, 1.0, v68
	v_add_f32_e32 v2, 1.0, v4
	v_rcp_f32_e32 v5, v2
	v_exp_f32_e32 v4, v69
	v_sub_f32_e32 v12, 1.0, v5
	v_add_f32_e32 v2, 1.0, v4
	v_rcp_f32_e32 v14, v2
	v_exp_f32_e32 v4, v70
	v_sub_f32_e32 v15, 1.0, v14
	v_add_f32_e32 v2, 1.0, v4
	v_rcp_f32_e32 v69, v2
	v_exp_f32_e32 v4, v71
	v_sub_f32_e32 v70, 1.0, v69
	v_add_f32_e32 v2, 1.0, v4
	v_rcp_f32_e32 v71, v2
	v_exp_f32_e32 v4, v72
	v_sub_f32_e32 v72, 1.0, v71
	v_add_f32_e32 v2, 1.0, v4
	v_rcp_f32_e32 v6, v2
	v_exp_f32_e32 v4, v73
	v_sub_f32_e32 v73, 1.0, v6
	v_add_f32_e32 v2, 1.0, v4
	v_rcp_f32_e32 v8, v2
	v_exp_f32_e32 v4, v74
	v_sub_f32_e32 v74, 1.0, v8
	v_add_f32_e32 v2, 1.0, v4
	v_exp_f32_e32 v4, v75
	v_rcp_f32_e32 v75, v2
	s_nop 0
	v_sub_f32_e32 v123, 1.0, v75
	v_add_f32_e32 v2, 1.0, v4
	v_exp_f32_e32 v4, v76
	v_rcp_f32_e32 v76, v2
	s_nop 0
	v_sub_f32_e32 v124, 1.0, v76
	v_add_f32_e32 v2, 1.0, v4
	v_rcp_f32_e32 v7, v2
	v_exp_f32_e32 v4, v77
	v_sub_f32_e32 v77, 1.0, v7
	v_add_f32_e32 v2, 1.0, v4
	v_exp_f32_e32 v4, v78
	v_rcp_f32_e32 v78, v2
	s_nop 0
	v_sub_f32_e32 v125, 1.0, v78
	v_add_f32_e32 v2, 1.0, v4
	v_exp_f32_e32 v4, v79
	v_rcp_f32_e32 v79, v2
	s_nop 0
	v_sub_f32_e32 v126, 1.0, v79
	v_add_f32_e32 v2, 1.0, v4
	v_rcp_f32_e32 v127, v2
	v_mul_f32_e32 v7, v7, v78
	v_sub_f32_e32 v128, 1.0, v127
	v_mul_f32_e32 v2, v3, v64
	v_mul_f32_e32 v3, v66, v68
	v_mul_f32_e32 v4, v2, v3
	v_mov_b32_e32 v2, v4
	v_mov_b32_e32 v3, v4
	s_nop 1
	v_permlane32_swap_b32_e32 v2, v3
	v_cndmask_b32_e64 v2, v2, v3, s[40:41]
	v_mul_f32_e32 v3, v5, v14
	v_mul_f32_e32 v5, v69, v71
	v_mul_f32_e32 v3, v3, v5
	v_mov_b32_e32 v5, v3
	v_mov_b32_e32 v9, v3
	s_nop 1
	v_permlane32_swap_b32_e32 v5, v9
	v_cndmask_b32_e64 v5, v5, v9, s[40:41]
	v_mul_f32_e32 v9, v79, v127
	v_pk_mul_f32 v[6:7], v[6:7], v[8:9]
	v_mul_f32_e32 v10, v75, v76
	v_mov_b32_e32 v9, v7
	v_mov_b32_e32 v11, v7
	s_nop 1
	v_permlane32_swap_b32_e32 v9, v11
	v_cndmask_b32_e64 v11, v9, v11, s[40:41]
	v_pk_mul_f32 v[6:7], v[6:7], v[10:11]
	s_nop 0
	v_mov_b32_e32 v9, v6
	v_mov_b32_e32 v10, v6
	s_nop 1
	v_permlane32_swap_b32_e32 v9, v10
	v_cndmask_b32_e64 v116, v9, v10, s[40:41]
	v_mul_f32_e32 v9, v117, v11
	v_cndmask_b32_e64 v9, v117, v9, s[40:41]
	v_mul_f32_e32 v128, v128, v9
	v_mul_f32_e32 v9, v127, v9
	v_mul_f32_e32 v126, v126, v9
	v_mul_f32_e32 v9, v79, v9
	v_mul_f32_e32 v79, v125, v9
	v_mul_f32_e32 v9, v78, v9
	v_pk_mul_f32 v[6:7], v[6:7], v[116:117]
; DI float half_other(float x, int hh) { float a, b; half_swap(x, a, b); return hh ? a : b; }
; DI int crow(int reg, int hh) { return (reg & 3) + 8 * (reg >> 2) + 4 * hh; }
; DI float ex2(float x) { return __builtin_amdgcn_exp2f(x); }
; DI void sb_item(const bf16_t* __restrict__ P, const bf16_t* __restrict__ VT, bf16_t* __restrict__ Y, int item, char* lds) {
;     ...
;         float st[16];
; #pragma unroll
;         for (int e = 0; e < 16; ++e) {
;           const float ez = ex2(S[kt2][e]);
;           const float r = __builtin_amdgcn_rcpf(1.f + ez);
;           const bool vis = full || (kb * 64 + kt2 * 32 + crow(e, hh) < qpos);
;           st[e] = vis ? r : 1.f;
;           S[kt2][e] = vis ? 1.f - r : 0.f;
;         }
;         float G[4], Go[4];
; #pragma unroll
;         for (int j = 0; j < 4; ++j) { G[j] = (st[4 * j] * st[4 * j + 1]) * (st[4 * j + 2] * st[4 * j + 3]); Go[j] = half_other(G[j], hh); }
;         float T = carry;
; #pragma unroll
;         for (int j = 3; j >= 0; --j) {
;           float run = hh ? T : T * Go[j];
; #pragma unroll
;           for (int e = 3; e >= 0; --e) {
;             const int idx = 4 * j + e;
;             S[kt2][idx] *= run;
;             run *= st[idx];
;           }
;           T *= G[j] * Go[j];
;         }
;         carry = T;
;       }
;       pv_tile(kcur + TS, S, O, l32, hh);
	v_mul_f32_e32 v77, v77, v9
	v_mul_f32_e32 v9, v7, v116
	v_pk_mul_f32 v[10:11], v[6:7], v[6:7] op_sel:[0,1] op_sel_hi:[1,0]
	v_cndmask_b32_e64 v9, v7, v9, s[40:41]
	v_mul_f32_e32 v6, v10, v5
	v_exp_f32_e32 v7, v48
	v_cndmask_b32_e64 v6, v10, v6, s[40:41]
	v_mul_f32_e32 v72, v72, v6
	v_mul_f32_e32 v6, v71, v6
	v_mul_f32_e32 v70, v70, v6
	v_mul_f32_e32 v6, v69, v6
	v_mul_f32_e32 v69, v15, v6
	v_mul_f32_e32 v6, v14, v6
	v_mul_f32_e32 v14, v3, v5
	v_add_f32_e32 v3, 1.0, v7
	v_rcp_f32_e32 v3, v3
	v_mul_f32_e32 v78, v124, v9
	v_mul_f32_e32 v9, v76, v9
	v_exp_f32_e32 v5, v49
	v_mul_f32_e32 v76, v123, v9
	v_mul_f32_e32 v9, v75, v9
	v_mul_f32_e32 v8, v8, v9
	v_mul_f32_e32 v73, v73, v8
	v_mov_b32_e32 v8, v3
	v_sub_f32_e32 v75, 1.0, v3
	v_add_f32_e32 v3, 1.0, v5
	v_rcp_f32_e32 v3, v3
	v_exp_f32_e32 v5, v50
	v_mul_f32_e32 v71, v12, v6
	v_mov_b32_e32 v6, v3
	v_sub_f32_e32 v116, 1.0, v3
	v_add_f32_e32 v3, 1.0, v5
	v_rcp_f32_e32 v12, v3
	v_exp_f32_e32 v5, v51
	v_sub_f32_e32 v117, 1.0, v12
	v_add_f32_e32 v3, 1.0, v5
	v_rcp_f32_e32 v48, v3
	v_exp_f32_e32 v5, v52
	v_sub_f32_e32 v123, 1.0, v48
	v_add_f32_e32 v3, 1.0, v5
	v_rcp_f32_e32 v7, v3
	v_exp_f32_e32 v5, v53
	v_sub_f32_e32 v124, 1.0, v7
	v_add_f32_e32 v3, 1.0, v5
	v_exp_f32_e32 v5, v54
	v_rcp_f32_e32 v54, v3
	s_nop 0
	v_sub_f32_e32 v125, 1.0, v54
	v_add_f32_e32 v3, 1.0, v5
	v_exp_f32_e32 v5, v55
	v_rcp_f32_e32 v55, v3
	s_nop 0
	v_sub_f32_e32 v127, 1.0, v55
	v_add_f32_e32 v3, 1.0, v5
	v_exp_f32_e32 v5, v56
	v_rcp_f32_e32 v56, v3
	s_nop 0
	v_sub_f32_e32 v129, 1.0, v56
	v_add_f32_e32 v3, 1.0, v5
	v_rcp_f32_e32 v49, v3
	v_exp_f32_e32 v5, v57
	v_sub_f32_e32 v52, 1.0, v49
	v_add_f32_e32 v3, 1.0, v5
	v_rcp_f32_e32 v53, v3
	v_exp_f32_e32 v5, v58
	v_sub_f32_e32 v57, 1.0, v53
	v_add_f32_e32 v3, 1.0, v5
	v_rcp_f32_e32 v58, v3
	v_exp_f32_e32 v5, v59
	v_sub_f32_e32 v59, 1.0, v58
	v_add_f32_e32 v3, 1.0, v5
	v_exp_f32_e32 v5, v60
	v_rcp_f32_e32 v60, v3
	s_nop 0
	v_sub_f32_e32 v130, 1.0, v60
	v_add_f32_e32 v3, 1.0, v5
	v_rcp_f32_e32 v5, v3
	v_mul_f32_e32 v74, v74, v9
	v_exp_f32_e32 v9, v61
	v_exp_f32_e32 v11, v62
	v_sub_f32_e32 v61, 1.0, v5
	v_add_f32_e32 v3, 1.0, v9
	v_rcp_f32_e32 v3, v3
	v_mul_f32_e32 v7, v7, v54
	v_sub_f32_e32 v62, 1.0, v3
	v_add_f32_e32 v9, 1.0, v11
	v_rcp_f32_e32 v15, v9
	v_exp_f32_e32 v11, v63
	v_sub_f32_e32 v63, 1.0, v15
	v_add_f32_e32 v9, 1.0, v11
	v_rcp_f32_e32 v11, v9
	s_nop 0
	v_sub_f32_e32 v13, 1.0, v11
	v_mul_f32_e32 v9, v55, v56
	v_mul_f32_e32 v9, v7, v9
	v_mov_b32_e32 v7, v9
	v_mov_b32_e32 v50, v9
	s_nop 1
	v_permlane32_swap_b32_e32 v7, v50
	v_cndmask_b32_e64 v7, v7, v50, s[40:41]
	v_mul_f32_e32 v49, v49, v53
	v_mul_f32_e32 v50, v58, v60
	v_mul_f32_e32 v131, v49, v50
	v_mov_b32_e32 v49, v131
	v_mov_b32_e32 v50, v131
	s_nop 1
	v_permlane32_swap_b32_e32 v49, v50
	v_cndmask_b32_e64 v132, v49, v50, s[40:41]
	v_pk_mul_f32 v[50:51], v[14:15], v[10:11]
	v_pk_mul_f32 v[4:5], v[4:5], v[2:3]
	v_mul_f32_e32 v10, v50, v2
	v_cndmask_b32_e64 v10, v50, v10, s[40:41]
	v_mul_f32_e32 v122, v122, v10
	v_mul_f32_e32 v10, v68, v10
	v_mul_f32_e32 v67, v67, v10
	v_mul_f32_e32 v10, v66, v10
	v_mul_f32_e32 v65, v65, v10
	v_mul_f32_e32 v10, v64, v10
	v_pk_mul_f32 v[4:5], v[4:5], v[50:51]
	v_mul_f32_e32 v0, v0, v10
	v_mov_b32_e32 v2, v5
	v_mov_b32_e32 v10, v5
	s_nop 1
	v_permlane32_swap_b32_e32 v2, v10
	v_cndmask_b32_e64 v2, v2, v10, s[40:41]
	v_mul_f32_e32 v10, v4, v2
	v_mul_f32_e32 v2, v5, v2
	v_mul_f32_e32 v49, v4, v2
	v_mul_f32_e32 v2, v49, v132
	v_cndmask_b32_e64 v10, v4, v10, s[40:41]
	v_cndmask_b32_e64 v2, v49, v2, s[40:41]
	v_mul_f32_e32 v64, v13, v10
	v_mul_f32_e32 v10, v11, v10
	v_mul_f32_e32 v66, v130, v2
	v_mul_f32_e32 v2, v60, v2
	v_mul_f32_e32 v63, v63, v10
	v_mul_f32_e32 v10, v15, v10
	v_mul_f32_e32 v59, v59, v2
	v_mul_f32_e32 v2, v58, v2
	v_mul_f32_e32 v3, v3, v10
	v_mul_f32_e32 v57, v57, v2
	v_mul_f32_e32 v2, v53, v2
	v_mul_f32_e32 v13, v131, v132
	v_mul_f32_e32 v61, v61, v3
	v_mul_f32_e32 v58, v52, v2
	v_pk_mul_f32 v[2:3], v[12:13], v[48:49]
	v_pk_mul_f32 v[4:5], v[8:9], v[6:7]
	v_mul_f32_e32 v62, v62, v10
	v_pk_mul_f32 v[52:53], v[4:5], v[2:3]
	s_nop 0
	v_mov_b32_e32 v2, v52
	v_mov_b32_e32 v4, v52
	s_nop 1
	v_permlane32_swap_b32_e32 v2, v4
	v_cndmask_b32_e64 v60, v2, v4, s[40:41]
	v_mul_f32_e32 v2, v3, v7
	v_cndmask_b32_e64 v2, v3, v2, s[40:41]
	v_mul_f32_e32 v7, v129, v2
	v_mul_f32_e32 v2, v56, v2
	v_mul_f32_e32 v56, v127, v2
	v_mul_f32_e32 v2, v55, v2
	v_mul_f32_e32 v55, v125, v2
	v_mul_f32_e32 v2, v54, v2
	v_mul_f32_e32 v54, v124, v2
	v_mul_f32_e32 v2, v53, v60
	v_cndmask_b32_e64 v2, v53, v2, s[40:41]
	v_mul_f32_e32 v68, v123, v2
	v_mul_f32_e32 v2, v48, v2
	v_mul_f32_e32 v123, v117, v2
	v_mul_f32_e32 v117, v12, v2
	v_lshlrev_b32_e32 v2, 1, v113
	v_lshlrev_b32_e32 v3, 1, v120
	v_add3_u32 v12, s14, v2, v3
	v_add_u32_e32 v124, 0x2000, v12
	v_add_u32_e32 v125, 0x3000, v12
	ds_read2_b64 v[2:5], v124 offset0:128 offset1:130
	ds_read2_b64 v[8:11], v124 offset0:132 offset1:134
	ds_read2_b64 v[12:15], v125 offset0:192 offset1:194
	ds_read2_b64 v[48:51], v125 offset0:196 offset1:198
	v_mul_f32_e32 v52, v52, v60
	v_mul_f32_e32 v116, v116, v117
	v_mul_f32_e32 v6, v6, v117
	v_mul_f32_e32 v117, v52, v53
	v_mul_f32_e32 v6, v75, v6
	s_branch .Lsb_join1

; DI int crow(int reg, int hh) { return (reg & 3) + 8 * (reg >> 2) + 4 * hh; }
; DI float ex2(float x) { return __builtin_amdgcn_exp2f(x); }
; DI void sb_item(const bf16_t* __restrict__ P, const bf16_t* __restrict__ VT, bf16_t* __restrict__ Y, int item, char* lds) {
;     ...
;   auto do_tile = [&](int kb, const bf16_t* kcur) {
;     const bool active = (kb * 64 < q0 + 31) && (__ballot(carry > 0.f) != 0ull);
;     if (active) {
;       qk_tile(kcur, qf, S, l32, hh);
;       const bool full = kb * 64 + 63 < q0;
; #pragma unroll
;     ...
;         float st[16];
; #pragma unroll
;         for (int e = 0; e < 16; ++e) {
;           const float ez = ex2(S[kt2][e]);
;           const float r = __builtin_amdgcn_rcpf(1.f + ez);
;           const bool vis = full || (kb * 64 + kt2 * 32 + crow(e, hh) < qpos);
;           st[e] = vis ? r : 1.f;
;           S[kt2][e] = vis ? 1.f - r : 0.f;
;         }
.LBB0_488:
	s_or_b64 exec, exec, s[48:49]
	s_add_i32 s0, s10, 0xffffff81
	v_cmp_lt_i32_e32 vcc, s0, v119
	s_and_saveexec_b64 s[48:49], vcc
	s_cbranch_execz .LBB0_491
	v_cmp_lt_f32_e32 vcc, 0, v117
	s_cbranch_vccz .LBB0_491
	v_lshl_add_u32 v0, v121, 1, s14
	ds_read_b128 v[2:5], v0 offset:18432
	ds_read_b128 v[6:9], v0 offset:18464
	ds_read_b128 v[10:13], v0 offset:18496
	ds_read_b128 v[122:125], v0 offset:18528
	ds_read_b128 v[64:67], v0 offset:23040
	ds_read_b128 v[126:129], v0 offset:23072
	ds_read_b128 v[130:133], v0 offset:23104
	ds_read_b128 v[134:137], v0 offset:23136
	s_setprio 1
	s_waitcnt lgkmcnt(7)
	v_mfma_f32_32x32x16_bf16 v[48:63], v[2:5], v[80:83], 0
	s_waitcnt lgkmcnt(3)
	v_mfma_f32_32x32x16_bf16 v[64:79], v[64:67], v[80:83], 0
	v_mfma_f32_32x32x16_bf16 v[48:63], v[6:9], v[84:87], v[48:63]
	s_waitcnt lgkmcnt(2)
	v_mfma_f32_32x32x16_bf16 v[64:79], v[126:129], v[84:87], v[64:79]
	v_mfma_f32_32x32x16_bf16 v[48:63], v[10:13], v[88:91], v[48:63]
	s_waitcnt lgkmcnt(1)
	v_mfma_f32_32x32x16_bf16 v[64:79], v[130:133], v[88:91], v[64:79]
	v_mfma_f32_32x32x16_bf16 v[48:63], v[122:125], v[92:95], v[48:63]
	s_waitcnt lgkmcnt(0)
	v_mfma_f32_32x32x16_bf16 v[64:79], v[134:137], v[92:95], v[64:79]
	s_setprio 0
	s_nop 10
	v_exp_f32_e32 v0, v64
	v_add_u32_e32 v13, s10, v113
	s_sub_i32 s0, s10, 64
	v_add_u32_e32 v2, 0xffffffa1, v13
	v_cmp_lt_i32_e32 vcc, s0, v118
	s_cmp_eq_u64 vcc, exec
	s_cbranch_scc0 .Lsb_slow2
	v_add_f32_e32 v0, 1.0, v0
	v_exp_f32_e32 v2, v65
	v_rcp_f32_e32 v3, v0
	v_add_f32_e32 v2, 1.0, v2
	v_sub_f32_e32 v0, 1.0, v3
	v_rcp_f32_e32 v64, v2
	v_exp_f32_e32 v4, v66
	v_sub_f32_e32 v65, 1.0, v64
	v_add_f32_e32 v2, 1.0, v4
	v_rcp_f32_e32 v66, v2
	v_exp_f32_e32 v4, v67
	v_sub_f32_e32 v67, 1.0, v66
	v_add_f32_e32 v2, 1.0, v4
	v_exp_f32_e32 v4, v68
	v_rcp_f32_e32 v68, v2
	s_nop 0
	v_sub_f32_e32 v122, 1.0, v68
	v_add_f32_e32 v2, 1.0, v4
	v_rcp_f32_e32 v5, v2
	v_exp_f32_e32 v4, v69
	v_sub_f32_e32 v12, 1.0, v5
	v_add_f32_e32 v2, 1.0, v4
	v_rcp_f32_e32 v14, v2
	v_exp_f32_e32 v4, v70
	v_sub_f32_e32 v15, 1.0, v14
	v_add_f32_e32 v2, 1.0, v4
	v_rcp_f32_e32 v69, v2
	v_exp_f32_e32 v4, v71
	v_sub_f32_e32 v70, 1.0, v69
	v_add_f32_e32 v2, 1.0, v4
	v_rcp_f32_e32 v71, v2
	v_exp_f32_e32 v4, v72
	v_sub_f32_e32 v72, 1.0, v71
	v_add_f32_e32 v2, 1.0, v4
	v_rcp_f32_e32 v6, v2
	v_exp_f32_e32 v4, v73
	v_sub_f32_e32 v73, 1.0, v6
	v_add_f32_e32 v2, 1.0, v4
	v_rcp_f32_e32 v8, v2
	v_exp_f32_e32 v4, v74
	v_sub_f32_e32 v74, 1.0, v8
	v_add_f32_e32 v2, 1.0, v4
	v_exp_f32_e32 v4, v75
	v_rcp_f32_e32 v75, v2
	s_nop 0
	v_sub_f32_e32 v123, 1.0, v75
	v_add_f32_e32 v2, 1.0, v4
	v_exp_f32_e32 v4, v76
	v_rcp_f32_e32 v76, v2
	s_nop 0
	v_sub_f32_e32 v124, 1.0, v76
	v_add_f32_e32 v2, 1.0, v4
	v_rcp_f32_e32 v7, v2
	v_exp_f32_e32 v4, v77
	v_sub_f32_e32 v77, 1.0, v7
	v_add_f32_e32 v2, 1.0, v4
	v_exp_f32_e32 v4, v78
	v_rcp_f32_e32 v78, v2
	s_nop 0
	v_sub_f32_e32 v125, 1.0, v78
	v_add_f32_e32 v2, 1.0, v4
	v_exp_f32_e32 v4, v79
	v_rcp_f32_e32 v79, v2
	s_nop 0
	v_sub_f32_e32 v126, 1.0, v79
	v_add_f32_e32 v2, 1.0, v4
	v_rcp_f32_e32 v127, v2
	v_mul_f32_e32 v7, v7, v78
	v_sub_f32_e32 v128, 1.0, v127
	v_mul_f32_e32 v2, v3, v64
	v_mul_f32_e32 v3, v66, v68
	v_mul_f32_e32 v4, v2, v3
	v_mov_b32_e32 v2, v4
	v_mov_b32_e32 v3, v4
	s_nop 1
	v_permlane32_swap_b32_e32 v2, v3
	v_cndmask_b32_e64 v2, v2, v3, s[40:41]
	v_mul_f32_e32 v3, v5, v14
	v_mul_f32_e32 v5, v69, v71
	v_mul_f32_e32 v3, v3, v5
	v_mov_b32_e32 v5, v3
	v_mov_b32_e32 v9, v3
	s_nop 1
	v_permlane32_swap_b32_e32 v5, v9
	v_cndmask_b32_e64 v5, v5, v9, s[40:41]
	v_mul_f32_e32 v9, v79, v127
	v_pk_mul_f32 v[6:7], v[6:7], v[8:9]
	v_mul_f32_e32 v10, v75, v76
	v_mov_b32_e32 v9, v7
	v_mov_b32_e32 v11, v7
	s_nop 1
	v_permlane32_swap_b32_e32 v9, v11
	v_cndmask_b32_e64 v11, v9, v11, s[40:41]
	v_pk_mul_f32 v[6:7], v[6:7], v[10:11]
	s_nop 0
	v_mov_b32_e32 v9, v6
	v_mov_b32_e32 v10, v6
	s_nop 1
	v_permlane32_swap_b32_e32 v9, v10
	v_cndmask_b32_e64 v116, v9, v10, s[40:41]
	v_mul_f32_e32 v9, v117, v11
	v_cndmask_b32_e64 v9, v117, v9, s[40:41]
	v_mul_f32_e32 v128, v128, v9
	v_mul_f32_e32 v9, v127, v9
	v_mul_f32_e32 v126, v126, v9
	v_mul_f32_e32 v9, v79, v9
	v_mul_f32_e32 v79, v125, v9
	v_mul_f32_e32 v9, v78, v9
	v_pk_mul_f32 v[6:7], v[6:7], v[116:117]
	v_mul_f32_e32 v77, v77, v9
	v_mul_f32_e32 v9, v7, v116
	v_pk_mul_f32 v[10:11], v[6:7], v[6:7] op_sel:[0,1] op_sel_hi:[1,0]
	v_cndmask_b32_e64 v9, v7, v9, s[40:41]
	v_mul_f32_e32 v6, v10, v5
	v_exp_f32_e32 v7, v48
	v_cndmask_b32_e64 v6, v10, v6, s[40:41]
	v_mul_f32_e32 v72, v72, v6
	v_mul_f32_e32 v6, v71, v6
	v_mul_f32_e32 v70, v70, v6
	v_mul_f32_e32 v6, v69, v6
	v_mul_f32_e32 v69, v15, v6
	v_mul_f32_e32 v6, v14, v6
	v_mul_f32_e32 v14, v3, v5
	v_add_f32_e32 v3, 1.0, v7
; DI float half_other(float x, int hh) { float a, b; half_swap(x, a, b); return hh ? a : b; }
; DI int crow(int reg, int hh) { return (reg & 3) + 8 * (reg >> 2) + 4 * hh; }
; DI float ex2(float x) { return __builtin_amdgcn_exp2f(x); }
; DI void sb_item(const bf16_t* __restrict__ P, const bf16_t* __restrict__ VT, bf16_t* __restrict__ Y, int item, char* lds) {
;     ...
;         float st[16];
; #pragma unroll
;         for (int e = 0; e < 16; ++e) {
;           const float ez = ex2(S[kt2][e]);
;           const float r = __builtin_amdgcn_rcpf(1.f + ez);
;           const bool vis = full || (kb * 64 + kt2 * 32 + crow(e, hh) < qpos);
;           st[e] = vis ? r : 1.f;
;           S[kt2][e] = vis ? 1.f - r : 0.f;
;         }
;         float G[4], Go[4];
; #pragma unroll
;         for (int j = 0; j < 4; ++j) { G[j] = (st[4 * j] * st[4 * j + 1]) * (st[4 * j + 2] * st[4 * j + 3]); Go[j] = half_other(G[j], hh); }
;         float T = carry;
; #pragma unroll
;         for (int j = 3; j >= 0; --j) {
;           float run = hh ? T : T * Go[j];
; #pragma unroll
;           for (int e = 3; e >= 0; --e) {
;             const int idx = 4 * j + e;
;             S[kt2][idx] *= run;
;             run *= st[idx];
;           }
;           T *= G[j] * Go[j];
;         }
;         carry = T;
;       }
;       pv_tile(kcur + TS, S, O, l32, hh);
	v_rcp_f32_e32 v3, v3
	v_mul_f32_e32 v78, v124, v9
	v_mul_f32_e32 v9, v76, v9
	v_exp_f32_e32 v5, v49
	v_mul_f32_e32 v76, v123, v9
	v_mul_f32_e32 v9, v75, v9
	v_mul_f32_e32 v8, v8, v9
	v_mul_f32_e32 v73, v73, v8
	v_mov_b32_e32 v8, v3
	v_sub_f32_e32 v75, 1.0, v3
	v_add_f32_e32 v3, 1.0, v5
	v_rcp_f32_e32 v3, v3
	v_exp_f32_e32 v5, v50
	v_mul_f32_e32 v71, v12, v6
	v_mov_b32_e32 v6, v3
	v_sub_f32_e32 v116, 1.0, v3
	v_add_f32_e32 v3, 1.0, v5
	v_rcp_f32_e32 v12, v3
	v_exp_f32_e32 v5, v51
	v_sub_f32_e32 v117, 1.0, v12
	v_add_f32_e32 v3, 1.0, v5
	v_rcp_f32_e32 v48, v3
	v_exp_f32_e32 v5, v52
	v_sub_f32_e32 v123, 1.0, v48
	v_add_f32_e32 v3, 1.0, v5
	v_rcp_f32_e32 v7, v3
	v_exp_f32_e32 v5, v53
	v_sub_f32_e32 v124, 1.0, v7
	v_add_f32_e32 v3, 1.0, v5
	v_exp_f32_e32 v5, v54
	v_rcp_f32_e32 v54, v3
	s_nop 0
	v_sub_f32_e32 v125, 1.0, v54
	v_add_f32_e32 v3, 1.0, v5
	v_exp_f32_e32 v5, v55
	v_rcp_f32_e32 v55, v3
	s_nop 0
	v_sub_f32_e32 v127, 1.0, v55
	v_add_f32_e32 v3, 1.0, v5
	v_exp_f32_e32 v5, v56
	v_rcp_f32_e32 v56, v3
	s_nop 0
	v_sub_f32_e32 v129, 1.0, v56
	v_add_f32_e32 v3, 1.0, v5
	v_rcp_f32_e32 v49, v3
	v_exp_f32_e32 v5, v57
	v_sub_f32_e32 v52, 1.0, v49
	v_add_f32_e32 v3, 1.0, v5
	v_rcp_f32_e32 v53, v3
	v_exp_f32_e32 v5, v58
	v_sub_f32_e32 v57, 1.0, v53
	v_add_f32_e32 v3, 1.0, v5
	v_rcp_f32_e32 v58, v3
	v_exp_f32_e32 v5, v59
	v_sub_f32_e32 v59, 1.0, v58
	v_add_f32_e32 v3, 1.0, v5
	v_exp_f32_e32 v5, v60
	v_rcp_f32_e32 v60, v3
	s_nop 0
	v_sub_f32_e32 v130, 1.0, v60
	v_add_f32_e32 v3, 1.0, v5
	v_rcp_f32_e32 v5, v3
	v_mul_f32_e32 v74, v74, v9
	v_exp_f32_e32 v9, v61
	v_exp_f32_e32 v11, v62
	v_sub_f32_e32 v61, 1.0, v5
	v_add_f32_e32 v3, 1.0, v9
	v_rcp_f32_e32 v3, v3
	v_mul_f32_e32 v7, v7, v54
	v_sub_f32_e32 v62, 1.0, v3
	v_add_f32_e32 v9, 1.0, v11
	v_rcp_f32_e32 v15, v9
	v_exp_f32_e32 v11, v63
	v_sub_f32_e32 v63, 1.0, v15
	v_add_f32_e32 v9, 1.0, v11
	v_rcp_f32_e32 v11, v9
	s_nop 0
	v_sub_f32_e32 v13, 1.0, v11
	v_mul_f32_e32 v9, v55, v56
	v_mul_f32_e32 v9, v7, v9
	v_mov_b32_e32 v7, v9
	v_mov_b32_e32 v50, v9
	s_nop 1
	v_permlane32_swap_b32_e32 v7, v50
	v_cndmask_b32_e64 v7, v7, v50, s[40:41]
	v_mul_f32_e32 v49, v49, v53
	v_mul_f32_e32 v50, v58, v60
	v_mul_f32_e32 v131, v49, v50
	v_mov_b32_e32 v49, v131
	v_mov_b32_e32 v50, v131
	s_nop 1
	v_permlane32_swap_b32_e32 v49, v50
	v_cndmask_b32_e64 v132, v49, v50, s[40:41]
	v_pk_mul_f32 v[50:51], v[14:15], v[10:11]
	v_pk_mul_f32 v[4:5], v[4:5], v[2:3]
	v_mul_f32_e32 v10, v50, v2
	v_cndmask_b32_e64 v10, v50, v10, s[40:41]
	v_mul_f32_e32 v122, v122, v10
	v_mul_f32_e32 v10, v68, v10
	v_mul_f32_e32 v67, v67, v10
	v_mul_f32_e32 v10, v66, v10
	v_mul_f32_e32 v65, v65, v10
	v_mul_f32_e32 v10, v64, v10
	v_pk_mul_f32 v[4:5], v[4:5], v[50:51]
	v_mul_f32_e32 v0, v0, v10
	v_mov_b32_e32 v2, v5
	v_mov_b32_e32 v10, v5
	s_nop 1
	v_permlane32_swap_b32_e32 v2, v10
	v_cndmask_b32_e64 v2, v2, v10, s[40:41]
	v_mul_f32_e32 v10, v4, v2
	v_mul_f32_e32 v2, v5, v2
	v_mul_f32_e32 v49, v4, v2
	v_mul_f32_e32 v2, v49, v132
	v_cndmask_b32_e64 v10, v4, v10, s[40:41]
	v_cndmask_b32_e64 v2, v49, v2, s[40:41]
	v_mul_f32_e32 v64, v13, v10
	v_mul_f32_e32 v10, v11, v10
	v_mul_f32_e32 v66, v130, v2
	v_mul_f32_e32 v2, v60, v2
	v_mul_f32_e32 v63, v63, v10
	v_mul_f32_e32 v10, v15, v10
	v_mul_f32_e32 v59, v59, v2
	v_mul_f32_e32 v2, v58, v2
	v_mul_f32_e32 v3, v3, v10
	v_mul_f32_e32 v57, v57, v2
	v_mul_f32_e32 v2, v53, v2
	v_mul_f32_e32 v13, v131, v132
	v_mul_f32_e32 v61, v61, v3
	v_mul_f32_e32 v58, v52, v2
	v_pk_mul_f32 v[2:3], v[12:13], v[48:49]
	v_pk_mul_f32 v[4:5], v[8:9], v[6:7]
	v_mul_f32_e32 v62, v62, v10
	v_pk_mul_f32 v[52:53], v[4:5], v[2:3]
	s_nop 0
	v_mov_b32_e32 v2, v52
	v_mov_b32_e32 v4, v52
	s_nop 1
	v_permlane32_swap_b32_e32 v2, v4
	v_cndmask_b32_e64 v60, v2, v4, s[40:41]
	v_mul_f32_e32 v2, v3, v7
	v_cndmask_b32_e64 v2, v3, v2, s[40:41]
	v_mul_f32_e32 v7, v129, v2
	v_mul_f32_e32 v2, v56, v2
	v_mul_f32_e32 v56, v127, v2
	v_mul_f32_e32 v2, v55, v2
	v_mul_f32_e32 v55, v125, v2
	v_mul_f32_e32 v2, v54, v2
	v_mul_f32_e32 v54, v124, v2
	v_mul_f32_e32 v2, v53, v60
	v_cndmask_b32_e64 v2, v53, v2, s[40:41]
	v_mul_f32_e32 v68, v123, v2
	v_mul_f32_e32 v2, v48, v2
	v_mul_f32_e32 v123, v117, v2
	v_mul_f32_e32 v117, v12, v2
	v_lshlrev_b32_e32 v2, 1, v113
	v_lshlrev_b32_e32 v3, 1, v120
	v_add3_u32 v12, s14, v2, v3
	v_add_u32_e32 v124, 0x6800, v12
	v_add_u32_e32 v125, 0x7800, v12
	ds_read2_b64 v[2:5], v124 offset0:128 offset1:130
	ds_read2_b64 v[8:11], v124 offset0:132 offset1:134
	ds_read2_b64 v[12:15], v125 offset0:192 offset1:194
	ds_read2_b64 v[48:51], v125 offset0:196 offset1:198
	v_mul_f32_e32 v52, v52, v60
	v_mul_f32_e32 v116, v116, v117
	v_mul_f32_e32 v6, v6, v117
	v_mul_f32_e32 v117, v52, v53
	v_mul_f32_e32 v6, v75, v6
	s_branch .Lsb_join2
